# phase-0 GEMV: weight-row loads requested before the SiLU stage (conditioning loads oldest, counted waits)
# baseline (speedup 1.0000x reference)
.LBB0_8:
	s_cmpk_gt_i32 s2, 0xbf
	s_cbranch_scc1 .Lgv_end
	s_load_dwordx2 s[30:31], s[8:9], 0x28
	s_load_dwordx2 s[28:29], s[8:9], 0x30
	s_load_dwordx2 s[34:35], s[8:9], 0x40
	s_load_dwordx2 s[36:37], s[8:9], 0x48
	s_cmpk_gt_i32 s2, 0x5f
	s_cselect_b32 s14, 1, 0
	s_mul_i32 s15, s14, 0x60
	s_sub_i32 s15, s2, s15
	s_lshl_b32 s15, s15, 6
	v_lshlrev_b32_e32 v10, 2, v1
	s_waitcnt lgkmcnt(0)
	global_load_dword v80, v10, s[28:29]
	global_load_dword v81, v10, s[28:29] offset:2048
	global_load_dword v82, v10, s[30:31]
	global_load_dword v83, v10, s[30:31] offset:2048
	v_add_u32_e32 v11, 0x1000, v10
	global_load_dword v84, v11, s[30:31]
	v_add_u32_e32 v11, 0x1800, v10
	global_load_dword v85, v11, s[30:31]
	v_add_u32_e32 v11, 0x2000, v10
	global_load_dword v86, v11, s[30:31]
	v_add_u32_e32 v11, 0x2800, v10
	global_load_dword v87, v11, s[30:31]
	v_add_u32_e32 v11, 0x3000, v10
	global_load_dword v88, v11, s[30:31]
	v_add_u32_e32 v11, 0x3800, v10
	global_load_dword v89, v11, s[30:31]
	v_readfirstlane_b32 s16, v1
	s_lshr_b32 s16, s16, 6
	v_and_b32_e32 v11, 63, v1
	v_and_b32_e32 v12, 15, v11
	v_lshrrev_b32_e32 v13, 4, v11
	v_lshlrev_b32_e32 v14, 4, v12
	s_lshl_b32 s17, s15, 2
	v_add_u32_e32 v14, s17, v14
	v_mul_u32_u24_e32 v11, 0xc0000, v13
	v_add_u32_e32 v14, v11, v14
	s_mul_i32 s20, s14, 0x1800000
	s_mul_i32 s21, s16, 0x300000
	s_add_u32 s20, s20, s21
	s_add_u32 s20, s12, s20
	s_addc_u32 s21, s13, 0
	v_lshl_add_u32 v11, s16, 2, v13
	v_lshlrev_b32_e32 v11, 7, v11
	v_mov_b32_e32 v100, 0
	v_mov_b32_e32 v101, 0
	v_mov_b32_e32 v102, 0
	v_mov_b32_e32 v103, 0
	v_mov_b32_e32 v104, 0
	v_mov_b32_e32 v105, 0
	v_mov_b32_e32 v106, 0
	v_mov_b32_e32 v107, 0
	v_mov_b32_e32 v108, 0
	v_mov_b32_e32 v109, 0
	v_mov_b32_e32 v110, 0
	v_mov_b32_e32 v111, 0
	v_mov_b32_e32 v112, 0
	v_mov_b32_e32 v113, 0
	v_mov_b32_e32 v114, 0
	v_mov_b32_e32 v115, 0
	v_mov_b32_e32 v116, 0
	v_mov_b32_e32 v117, 0
	v_mov_b32_e32 v118, 0
	v_mov_b32_e32 v119, 0
	global_load_dwordx4 v[16:19], v14, s[20:21] nt
	s_add_u32 s20, s20, 0x6000
	s_addc_u32 s21, s21, 0
	global_load_dwordx4 v[20:23], v14, s[20:21] nt
	s_add_u32 s20, s20, 0x6000
	s_addc_u32 s21, s21, 0
	global_load_dwordx4 v[24:27], v14, s[20:21] nt
	s_add_u32 s20, s20, 0x6000
	s_addc_u32 s21, s21, 0
	global_load_dwordx4 v[28:31], v14, s[20:21] nt
	s_add_u32 s20, s20, 0x6000
	s_addc_u32 s21, s21, 0
	global_load_dwordx4 v[32:35], v14, s[20:21] nt
	s_add_u32 s20, s20, 0x6000
	s_addc_u32 s21, s21, 0
	global_load_dwordx4 v[36:39], v14, s[20:21] nt
	s_add_u32 s20, s20, 0x6000
	s_addc_u32 s21, s21, 0
	global_load_dwordx4 v[40:43], v14, s[20:21] nt
	s_add_u32 s20, s20, 0x6000
	s_addc_u32 s21, s21, 0
	global_load_dwordx4 v[44:47], v14, s[20:21] nt
	s_add_u32 s20, s20, 0x6000
	s_addc_u32 s21, s21, 0
	global_load_dwordx4 v[48:51], v14, s[20:21] nt
	s_add_u32 s20, s20, 0x6000
	s_addc_u32 s21, s21, 0
	global_load_dwordx4 v[52:55], v14, s[20:21] nt
	s_add_u32 s20, s20, 0x6000
	s_addc_u32 s21, s21, 0
	global_load_dwordx4 v[56:59], v14, s[20:21] nt
	s_add_u32 s20, s20, 0x6000
	s_addc_u32 s21, s21, 0
	global_load_dwordx4 v[60:63], v14, s[20:21] nt
	s_add_u32 s20, s20, 0x6000
	s_addc_u32 s21, s21, 0
	global_load_dwordx4 v[64:67], v14, s[20:21] nt
	s_add_u32 s20, s20, 0x6000
	s_addc_u32 s21, s21, 0
	global_load_dwordx4 v[68:71], v14, s[20:21] nt
	s_add_u32 s20, s20, 0x6000
	s_addc_u32 s21, s21, 0
	global_load_dwordx4 v[72:75], v14, s[20:21] nt
	s_add_u32 s20, s20, 0x6000
	s_addc_u32 s21, s21, 0
	global_load_dwordx4 v[76:79], v14, s[20:21] nt
	s_add_u32 s20, s20, 0x6000
	s_addc_u32 s21, s21, 0
	global_load_dwordx4 v[196:199], v14, s[20:21] nt
	s_add_u32 s20, s20, 0x6000
	s_addc_u32 s21, s21, 0
	global_load_dwordx4 v[200:203], v14, s[20:21] nt
	s_add_u32 s20, s20, 0x6000
	s_addc_u32 s21, s21, 0
	global_load_dwordx4 v[204:207], v14, s[20:21] nt
	s_add_u32 s20, s20, 0x6000
	s_addc_u32 s21, s21, 0
	global_load_dwordx4 v[208:211], v14, s[20:21] nt
	s_add_u32 s20, s20, 0x6000
	s_addc_u32 s21, s21, 0
	global_load_dwordx4 v[212:215], v14, s[20:21] nt
	s_add_u32 s20, s20, 0x6000
	s_addc_u32 s21, s21, 0
	global_load_dwordx4 v[216:219], v14, s[20:21] nt
	s_add_u32 s20, s20, 0x6000
	s_addc_u32 s21, s21, 0
	global_load_dwordx4 v[220:223], v14, s[20:21] nt
	s_add_u32 s20, s20, 0x6000
	s_addc_u32 s21, s21, 0
	global_load_dwordx4 v[224:227], v14, s[20:21] nt
	s_add_u32 s20, s20, 0x6000
	s_addc_u32 s21, s21, 0
	global_load_dwordx4 v[228:231], v14, s[20:21] nt
	s_add_u32 s20, s20, 0x6000
	s_addc_u32 s21, s21, 0
	global_load_dwordx4 v[96:99], v14, s[20:21] nt
	s_add_u32 s20, s20, 0x6000
	s_addc_u32 s21, s21, 0
	s_waitcnt vmcnt(35)
	v_mov_b32_e32 v2, v80
	v_mul_f32_e32 v4, 0xbfb8aa3b, v2
	v_rndne_f32_e32 v5, v4
	v_fma_f32 v6, v2, s3, -v4
	v_sub_f32_e32 v4, v4, v5
	v_fmac_f32_e32 v6, 0xb2a5705f, v2
	v_add_f32_e32 v4, v4, v6
	v_cvt_i32_f32_e32 v5, v5
	v_exp_f32_e32 v4, v4
	v_cmp_nlt_f32_e32 vcc, s18, v2
	v_ldexp_f32 v4, v4, v5
	s_nop 0
	v_cndmask_b32_e32 v4, 0, v4, vcc
	v_cmp_ngt_f32_e32 vcc, s19, v2
	s_nop 1
	v_cndmask_b32_e32 v4, v15, v4, vcc
	v_add_f32_e32 v4, 1.0, v4
	v_div_scale_f32 v5, s[22:23], v4, v4, v2
	v_rcp_f32_e32 v6, v5
	v_div_scale_f32 v7, vcc, v2, v4, v2
	v_fma_f32 v8, -v5, v6, 1.0
	v_fmac_f32_e32 v6, v8, v6
	v_mul_f32_e32 v8, v7, v6
	v_fma_f32 v9, -v5, v8, v7
	v_fmac_f32_e32 v8, v9, v6
	v_fma_f32 v5, -v5, v8, v7
	v_div_fmas_f32 v5, v5, v6, v8
	v_div_fixup_f32 v2, v5, v4, v2
	ds_write_b32 v10, v2
	s_waitcnt vmcnt(34)
	v_mov_b32_e32 v2, v81
	v_mul_f32_e32 v4, 0xbfb8aa3b, v2
	v_rndne_f32_e32 v5, v4
	v_fma_f32 v6, v2, s3, -v4
	v_sub_f32_e32 v4, v4, v5
	v_fmac_f32_e32 v6, 0xb2a5705f, v2
	v_add_f32_e32 v4, v4, v6
	v_cvt_i32_f32_e32 v5, v5
	v_exp_f32_e32 v4, v4
	v_cmp_nlt_f32_e32 vcc, s18, v2
	v_ldexp_f32 v4, v4, v5
	s_nop 0
	v_cndmask_b32_e32 v4, 0, v4, vcc
	v_cmp_ngt_f32_e32 vcc, s19, v2
	s_nop 1
	v_cndmask_b32_e32 v4, v15, v4, vcc
	v_add_f32_e32 v4, 1.0, v4
	v_div_scale_f32 v5, s[22:23], v4, v4, v2
	v_rcp_f32_e32 v6, v5
	v_div_scale_f32 v7, vcc, v2, v4, v2
	v_fma_f32 v8, -v5, v6, 1.0
	v_fmac_f32_e32 v6, v8, v6
	v_mul_f32_e32 v8, v7, v6
	v_fma_f32 v9, -v5, v8, v7
	v_fmac_f32_e32 v8, v9, v6
	v_fma_f32 v5, -v5, v8, v7
	v_div_fmas_f32 v5, v5, v6, v8
	v_div_fixup_f32 v2, v5, v4, v2
	ds_write_b32 v10, v2 offset:2048
	s_waitcnt vmcnt(33)
	v_mov_b32_e32 v2, v82
	v_mul_f32_e32 v4, 0xbfb8aa3b, v2
	v_rndne_f32_e32 v5, v4
	v_fma_f32 v6, v2, s3, -v4
	v_sub_f32_e32 v4, v4, v5
	v_fmac_f32_e32 v6, 0xb2a5705f, v2
	v_add_f32_e32 v4, v4, v6
	v_cvt_i32_f32_e32 v5, v5
	v_exp_f32_e32 v4, v4
	v_cmp_nlt_f32_e32 vcc, s18, v2
	v_ldexp_f32 v4, v4, v5
	s_nop 0
	v_cndmask_b32_e32 v4, 0, v4, vcc
	v_cmp_ngt_f32_e32 vcc, s19, v2
	s_nop 1
	v_cndmask_b32_e32 v4, v15, v4, vcc
	v_add_f32_e32 v4, 1.0, v4
	v_div_scale_f32 v5, s[22:23], v4, v4, v2
	v_rcp_f32_e32 v6, v5
	v_div_scale_f32 v7, vcc, v2, v4, v2
	v_fma_f32 v8, -v5, v6, 1.0
	v_fmac_f32_e32 v6, v8, v6
	v_mul_f32_e32 v8, v7, v6
	v_fma_f32 v9, -v5, v8, v7
	v_fmac_f32_e32 v8, v9, v6
	v_fma_f32 v5, -v5, v8, v7
	v_div_fmas_f32 v5, v5, v6, v8
	v_div_fixup_f32 v2, v5, v4, v2
	ds_write_b32 v10, v2 offset:4096
	s_waitcnt vmcnt(32)
	v_mov_b32_e32 v2, v83
	v_mul_f32_e32 v4, 0xbfb8aa3b, v2
	v_rndne_f32_e32 v5, v4
	v_fma_f32 v6, v2, s3, -v4
	v_sub_f32_e32 v4, v4, v5
	v_fmac_f32_e32 v6, 0xb2a5705f, v2
	v_add_f32_e32 v4, v4, v6
	v_cvt_i32_f32_e32 v5, v5
	v_exp_f32_e32 v4, v4
	v_cmp_nlt_f32_e32 vcc, s18, v2
	v_ldexp_f32 v4, v4, v5
	s_nop 0
	v_cndmask_b32_e32 v4, 0, v4, vcc
	v_cmp_ngt_f32_e32 vcc, s19, v2
	s_nop 1
	v_cndmask_b32_e32 v4, v15, v4, vcc
	v_add_f32_e32 v4, 1.0, v4
	v_div_scale_f32 v5, s[22:23], v4, v4, v2
	v_rcp_f32_e32 v6, v5
	v_div_scale_f32 v7, vcc, v2, v4, v2
	v_fma_f32 v8, -v5, v6, 1.0
	v_fmac_f32_e32 v6, v8, v6
	v_mul_f32_e32 v8, v7, v6
	v_fma_f32 v9, -v5, v8, v7
	v_fmac_f32_e32 v8, v9, v6
	v_fma_f32 v5, -v5, v8, v7
	v_div_fmas_f32 v5, v5, v6, v8
	v_div_fixup_f32 v2, v5, v4, v2
	ds_write_b32 v10, v2 offset:6144
	s_waitcnt vmcnt(31)
	v_mov_b32_e32 v2, v84
	v_mul_f32_e32 v4, 0xbfb8aa3b, v2
	v_rndne_f32_e32 v5, v4
	v_fma_f32 v6, v2, s3, -v4
	v_sub_f32_e32 v4, v4, v5
	v_fmac_f32_e32 v6, 0xb2a5705f, v2
	v_add_f32_e32 v4, v4, v6
	v_cvt_i32_f32_e32 v5, v5
	v_exp_f32_e32 v4, v4
	v_cmp_nlt_f32_e32 vcc, s18, v2
	v_ldexp_f32 v4, v4, v5
	s_nop 0
	v_cndmask_b32_e32 v4, 0, v4, vcc
	v_cmp_ngt_f32_e32 vcc, s19, v2
	s_nop 1
	v_cndmask_b32_e32 v4, v15, v4, vcc
	v_add_f32_e32 v4, 1.0, v4
	v_div_scale_f32 v5, s[22:23], v4, v4, v2
	v_rcp_f32_e32 v6, v5
	v_div_scale_f32 v7, vcc, v2, v4, v2
	v_fma_f32 v8, -v5, v6, 1.0
	v_fmac_f32_e32 v6, v8, v6
	v_mul_f32_e32 v8, v7, v6
	v_fma_f32 v9, -v5, v8, v7
	v_fmac_f32_e32 v8, v9, v6
	v_fma_f32 v5, -v5, v8, v7
	v_div_fmas_f32 v5, v5, v6, v8
	v_div_fixup_f32 v2, v5, v4, v2
	ds_write_b32 v10, v2 offset:8192
	s_waitcnt vmcnt(30)
	v_mov_b32_e32 v2, v85
	v_mul_f32_e32 v4, 0xbfb8aa3b, v2
	v_rndne_f32_e32 v5, v4
	v_fma_f32 v6, v2, s3, -v4
	v_sub_f32_e32 v4, v4, v5
	v_fmac_f32_e32 v6, 0xb2a5705f, v2
	v_add_f32_e32 v4, v4, v6
	v_cvt_i32_f32_e32 v5, v5
	v_exp_f32_e32 v4, v4
	v_cmp_nlt_f32_e32 vcc, s18, v2
	v_ldexp_f32 v4, v4, v5
	s_nop 0
	v_cndmask_b32_e32 v4, 0, v4, vcc
	v_cmp_ngt_f32_e32 vcc, s19, v2
	s_nop 1
	v_cndmask_b32_e32 v4, v15, v4, vcc
	v_add_f32_e32 v4, 1.0, v4
	v_div_scale_f32 v5, s[22:23], v4, v4, v2
	v_rcp_f32_e32 v6, v5
	v_div_scale_f32 v7, vcc, v2, v4, v2
	v_fma_f32 v8, -v5, v6, 1.0
	v_fmac_f32_e32 v6, v8, v6
	v_mul_f32_e32 v8, v7, v6
	v_fma_f32 v9, -v5, v8, v7
	v_fmac_f32_e32 v8, v9, v6
	v_fma_f32 v5, -v5, v8, v7
	v_div_fmas_f32 v5, v5, v6, v8
	v_div_fixup_f32 v2, v5, v4, v2
	ds_write_b32 v10, v2 offset:10240
	s_waitcnt vmcnt(29)
	v_mov_b32_e32 v2, v86
	v_mul_f32_e32 v4, 0xbfb8aa3b, v2
	v_rndne_f32_e32 v5, v4
	v_fma_f32 v6, v2, s3, -v4
	v_sub_f32_e32 v4, v4, v5
	v_fmac_f32_e32 v6, 0xb2a5705f, v2
	v_add_f32_e32 v4, v4, v6
	v_cvt_i32_f32_e32 v5, v5
	v_exp_f32_e32 v4, v4
	v_cmp_nlt_f32_e32 vcc, s18, v2
	v_ldexp_f32 v4, v4, v5
	s_nop 0
	v_cndmask_b32_e32 v4, 0, v4, vcc
	v_cmp_ngt_f32_e32 vcc, s19, v2
	s_nop 1
	v_cndmask_b32_e32 v4, v15, v4, vcc
	v_add_f32_e32 v4, 1.0, v4
	v_div_scale_f32 v5, s[22:23], v4, v4, v2
	v_rcp_f32_e32 v6, v5
	v_div_scale_f32 v7, vcc, v2, v4, v2
	v_fma_f32 v8, -v5, v6, 1.0
	v_fmac_f32_e32 v6, v8, v6
	v_mul_f32_e32 v8, v7, v6
	v_fma_f32 v9, -v5, v8, v7
	v_fmac_f32_e32 v8, v9, v6
	v_fma_f32 v5, -v5, v8, v7
	v_div_fmas_f32 v5, v5, v6, v8
	v_div_fixup_f32 v2, v5, v4, v2
	ds_write_b32 v10, v2 offset:12288
	s_waitcnt vmcnt(28)
	v_mov_b32_e32 v2, v87
	v_mul_f32_e32 v4, 0xbfb8aa3b, v2
	v_rndne_f32_e32 v5, v4
	v_fma_f32 v6, v2, s3, -v4
	v_sub_f32_e32 v4, v4, v5
	v_fmac_f32_e32 v6, 0xb2a5705f, v2
	v_add_f32_e32 v4, v4, v6
	v_cvt_i32_f32_e32 v5, v5
	v_exp_f32_e32 v4, v4
	v_cmp_nlt_f32_e32 vcc, s18, v2
	v_ldexp_f32 v4, v4, v5
	s_nop 0
	v_cndmask_b32_e32 v4, 0, v4, vcc
	v_cmp_ngt_f32_e32 vcc, s19, v2
	s_nop 1
	v_cndmask_b32_e32 v4, v15, v4, vcc
	v_add_f32_e32 v4, 1.0, v4
	v_div_scale_f32 v5, s[22:23], v4, v4, v2
	v_rcp_f32_e32 v6, v5
	v_div_scale_f32 v7, vcc, v2, v4, v2
	v_fma_f32 v8, -v5, v6, 1.0
	v_fmac_f32_e32 v6, v8, v6
	v_mul_f32_e32 v8, v7, v6
	v_fma_f32 v9, -v5, v8, v7
	v_fmac_f32_e32 v8, v9, v6
	v_fma_f32 v5, -v5, v8, v7
	v_div_fmas_f32 v5, v5, v6, v8
	v_div_fixup_f32 v2, v5, v4, v2
	ds_write_b32 v10, v2 offset:14336
	s_waitcnt vmcnt(27)
	v_mov_b32_e32 v2, v88
	v_mul_f32_e32 v4, 0xbfb8aa3b, v2
	v_rndne_f32_e32 v5, v4
	v_fma_f32 v6, v2, s3, -v4
	v_sub_f32_e32 v4, v4, v5
	v_fmac_f32_e32 v6, 0xb2a5705f, v2
	v_add_f32_e32 v4, v4, v6
	v_cvt_i32_f32_e32 v5, v5
	v_exp_f32_e32 v4, v4
	v_cmp_nlt_f32_e32 vcc, s18, v2
	v_ldexp_f32 v4, v4, v5
	s_nop 0
	v_cndmask_b32_e32 v4, 0, v4, vcc
	v_cmp_ngt_f32_e32 vcc, s19, v2
	s_nop 1
	v_cndmask_b32_e32 v4, v15, v4, vcc
	v_add_f32_e32 v4, 1.0, v4
	v_div_scale_f32 v5, s[22:23], v4, v4, v2
	v_rcp_f32_e32 v6, v5
	v_div_scale_f32 v7, vcc, v2, v4, v2
	v_fma_f32 v8, -v5, v6, 1.0
	v_fmac_f32_e32 v6, v8, v6
	v_mul_f32_e32 v8, v7, v6
	v_fma_f32 v9, -v5, v8, v7
	v_fmac_f32_e32 v8, v9, v6
	v_fma_f32 v5, -v5, v8, v7
	v_div_fmas_f32 v5, v5, v6, v8
	v_div_fixup_f32 v2, v5, v4, v2
	ds_write_b32 v10, v2 offset:16384
	s_waitcnt vmcnt(26)
	v_mov_b32_e32 v2, v89
	v_mul_f32_e32 v4, 0xbfb8aa3b, v2
	v_rndne_f32_e32 v5, v4
	v_fma_f32 v6, v2, s3, -v4
	v_sub_f32_e32 v4, v4, v5
	v_fmac_f32_e32 v6, 0xb2a5705f, v2
	v_add_f32_e32 v4, v4, v6
	v_cvt_i32_f32_e32 v5, v5
	v_exp_f32_e32 v4, v4
	v_cmp_nlt_f32_e32 vcc, s18, v2
	v_ldexp_f32 v4, v4, v5
	s_nop 0
	v_cndmask_b32_e32 v4, 0, v4, vcc
	v_cmp_ngt_f32_e32 vcc, s19, v2
	s_nop 1
	v_cndmask_b32_e32 v4, v15, v4, vcc
	v_add_f32_e32 v4, 1.0, v4
	v_div_scale_f32 v5, s[22:23], v4, v4, v2
	v_rcp_f32_e32 v6, v5
	v_div_scale_f32 v7, vcc, v2, v4, v2
	v_fma_f32 v8, -v5, v6, 1.0
	v_fmac_f32_e32 v6, v8, v6
	v_mul_f32_e32 v8, v7, v6
	v_fma_f32 v9, -v5, v8, v7
	v_fmac_f32_e32 v8, v9, v6
	v_fma_f32 v5, -v5, v8, v7
	v_div_fmas_f32 v5, v5, v6, v8
	v_div_fixup_f32 v2, v5, v4, v2
	ds_write_b32 v10, v2 offset:18432
	s_waitcnt lgkmcnt(0)
	s_barrier
	ds_read_b128 v[80:83], v11 offset:0
	ds_read_b128 v[84:87], v11 offset:16
	ds_read_b128 v[88:91], v11 offset:32
	ds_read_b128 v[92:95], v11 offset:48
	ds_read_b128 v[120:123], v11 offset:4096
	ds_read_b128 v[124:127], v11 offset:4112
	ds_read_b128 v[128:131], v11 offset:4128
	ds_read_b128 v[132:135], v11 offset:4144
	ds_read_b128 v[136:139], v11 offset:8192
	ds_read_b128 v[140:143], v11 offset:8208
	ds_read_b128 v[144:147], v11 offset:8224
	ds_read_b128 v[148:151], v11 offset:8240
	ds_read_b128 v[152:155], v11 offset:12288
	ds_read_b128 v[156:159], v11 offset:12304
	ds_read_b128 v[160:163], v11 offset:12320
	ds_read_b128 v[164:167], v11 offset:12336
	ds_read_b128 v[180:183], v11 offset:16384
	ds_read_b128 v[184:187], v11 offset:16400
	ds_read_b128 v[188:191], v11 offset:16416
	ds_read_b128 v[192:195], v11 offset:16432
	s_waitcnt lgkmcnt(0)
	s_waitcnt vmcnt(25)
	v_fmac_f32_e32 v100, v16, v80
	v_fmac_f32_e32 v101, v17, v80
	v_fmac_f32_e32 v102, v18, v80
	v_fmac_f32_e32 v103, v19, v80
	v_fmac_f32_e32 v104, v16, v120
	v_fmac_f32_e32 v105, v17, v120
	v_fmac_f32_e32 v106, v18, v120
	v_fmac_f32_e32 v107, v19, v120
	v_fmac_f32_e32 v108, v16, v136
	v_fmac_f32_e32 v109, v17, v136
	v_fmac_f32_e32 v110, v18, v136
	v_fmac_f32_e32 v111, v19, v136
	v_fmac_f32_e32 v112, v16, v152
	v_fmac_f32_e32 v113, v17, v152
	v_fmac_f32_e32 v114, v18, v152
	v_fmac_f32_e32 v115, v19, v152
	v_fmac_f32_e32 v116, v16, v180
	v_fmac_f32_e32 v117, v17, v180
	v_fmac_f32_e32 v118, v18, v180
	v_fmac_f32_e32 v119, v19, v180
	s_waitcnt vmcnt(24)
	v_fmac_f32_e32 v100, v20, v81
	v_fmac_f32_e32 v101, v21, v81
	v_fmac_f32_e32 v102, v22, v81
	v_fmac_f32_e32 v103, v23, v81
	v_fmac_f32_e32 v104, v20, v121
	v_fmac_f32_e32 v105, v21, v121
	v_fmac_f32_e32 v106, v22, v121
	v_fmac_f32_e32 v107, v23, v121
	v_fmac_f32_e32 v108, v20, v137
	v_fmac_f32_e32 v109, v21, v137
	v_fmac_f32_e32 v110, v22, v137
	v_fmac_f32_e32 v111, v23, v137
	v_fmac_f32_e32 v112, v20, v153
	v_fmac_f32_e32 v113, v21, v153
	v_fmac_f32_e32 v114, v22, v153
	v_fmac_f32_e32 v115, v23, v153
	v_fmac_f32_e32 v116, v20, v181
	v_fmac_f32_e32 v117, v21, v181
	v_fmac_f32_e32 v118, v22, v181
	v_fmac_f32_e32 v119, v23, v181
	s_waitcnt vmcnt(23)
	v_fmac_f32_e32 v100, v24, v82
	v_fmac_f32_e32 v101, v25, v82
	v_fmac_f32_e32 v102, v26, v82
	v_fmac_f32_e32 v103, v27, v82
	v_fmac_f32_e32 v104, v24, v122
	v_fmac_f32_e32 v105, v25, v122
	v_fmac_f32_e32 v106, v26, v122
	v_fmac_f32_e32 v107, v27, v122
	v_fmac_f32_e32 v108, v24, v138
	v_fmac_f32_e32 v109, v25, v138
	v_fmac_f32_e32 v110, v26, v138
	v_fmac_f32_e32 v111, v27, v138
	v_fmac_f32_e32 v112, v24, v154
	v_fmac_f32_e32 v113, v25, v154
	v_fmac_f32_e32 v114, v26, v154
	v_fmac_f32_e32 v115, v27, v154
	v_fmac_f32_e32 v116, v24, v182
	v_fmac_f32_e32 v117, v25, v182
	v_fmac_f32_e32 v118, v26, v182
	v_fmac_f32_e32 v119, v27, v182
	s_waitcnt vmcnt(22)
	v_fmac_f32_e32 v100, v28, v83
	v_fmac_f32_e32 v101, v29, v83
	v_fmac_f32_e32 v102, v30, v83
	v_fmac_f32_e32 v103, v31, v83
	v_fmac_f32_e32 v104, v28, v123
	v_fmac_f32_e32 v105, v29, v123
	v_fmac_f32_e32 v106, v30, v123
	v_fmac_f32_e32 v107, v31, v123
	v_fmac_f32_e32 v108, v28, v139
	v_fmac_f32_e32 v109, v29, v139
	v_fmac_f32_e32 v110, v30, v139
	v_fmac_f32_e32 v111, v31, v139
	v_fmac_f32_e32 v112, v28, v155
	v_fmac_f32_e32 v113, v29, v155
	v_fmac_f32_e32 v114, v30, v155
	v_fmac_f32_e32 v115, v31, v155
	v_fmac_f32_e32 v116, v28, v183
	v_fmac_f32_e32 v117, v29, v183
	v_fmac_f32_e32 v118, v30, v183
	v_fmac_f32_e32 v119, v31, v183
	s_waitcnt vmcnt(21)
	v_fmac_f32_e32 v100, v32, v84
	v_fmac_f32_e32 v101, v33, v84
	v_fmac_f32_e32 v102, v34, v84
	v_fmac_f32_e32 v103, v35, v84
	v_fmac_f32_e32 v104, v32, v124
	v_fmac_f32_e32 v105, v33, v124
	v_fmac_f32_e32 v106, v34, v124
	v_fmac_f32_e32 v107, v35, v124
	v_fmac_f32_e32 v108, v32, v140
	v_fmac_f32_e32 v109, v33, v140
	v_fmac_f32_e32 v110, v34, v140
	v_fmac_f32_e32 v111, v35, v140
	v_fmac_f32_e32 v112, v32, v156
	v_fmac_f32_e32 v113, v33, v156
	v_fmac_f32_e32 v114, v34, v156
	v_fmac_f32_e32 v115, v35, v156
	v_fmac_f32_e32 v116, v32, v184
	v_fmac_f32_e32 v117, v33, v184
	v_fmac_f32_e32 v118, v34, v184
	v_fmac_f32_e32 v119, v35, v184
	s_waitcnt vmcnt(20)
	v_fmac_f32_e32 v100, v36, v85
	v_fmac_f32_e32 v101, v37, v85
	v_fmac_f32_e32 v102, v38, v85
	v_fmac_f32_e32 v103, v39, v85
	v_fmac_f32_e32 v104, v36, v125
	v_fmac_f32_e32 v105, v37, v125
	v_fmac_f32_e32 v106, v38, v125
	v_fmac_f32_e32 v107, v39, v125
	v_fmac_f32_e32 v108, v36, v141
	v_fmac_f32_e32 v109, v37, v141
	v_fmac_f32_e32 v110, v38, v141
	v_fmac_f32_e32 v111, v39, v141
	v_fmac_f32_e32 v112, v36, v157
	v_fmac_f32_e32 v113, v37, v157
	v_fmac_f32_e32 v114, v38, v157
	v_fmac_f32_e32 v115, v39, v157
	v_fmac_f32_e32 v116, v36, v185
	v_fmac_f32_e32 v117, v37, v185
	v_fmac_f32_e32 v118, v38, v185
	v_fmac_f32_e32 v119, v39, v185
	s_waitcnt vmcnt(19)
	v_fmac_f32_e32 v100, v40, v86
	v_fmac_f32_e32 v101, v41, v86
	v_fmac_f32_e32 v102, v42, v86
	v_fmac_f32_e32 v103, v43, v86
	v_fmac_f32_e32 v104, v40, v126
	v_fmac_f32_e32 v105, v41, v126
	v_fmac_f32_e32 v106, v42, v126
	v_fmac_f32_e32 v107, v43, v126
	v_fmac_f32_e32 v108, v40, v142
	v_fmac_f32_e32 v109, v41, v142
	v_fmac_f32_e32 v110, v42, v142
	v_fmac_f32_e32 v111, v43, v142
	v_fmac_f32_e32 v112, v40, v158
	v_fmac_f32_e32 v113, v41, v158
	v_fmac_f32_e32 v114, v42, v158
	v_fmac_f32_e32 v115, v43, v158
	v_fmac_f32_e32 v116, v40, v186
	v_fmac_f32_e32 v117, v41, v186
	v_fmac_f32_e32 v118, v42, v186
	v_fmac_f32_e32 v119, v43, v186
	s_waitcnt vmcnt(18)
	v_fmac_f32_e32 v100, v44, v87
	v_fmac_f32_e32 v101, v45, v87
	v_fmac_f32_e32 v102, v46, v87
	v_fmac_f32_e32 v103, v47, v87
	v_fmac_f32_e32 v104, v44, v127
	v_fmac_f32_e32 v105, v45, v127
	v_fmac_f32_e32 v106, v46, v127
	v_fmac_f32_e32 v107, v47, v127
	v_fmac_f32_e32 v108, v44, v143
	v_fmac_f32_e32 v109, v45, v143
	v_fmac_f32_e32 v110, v46, v143
	v_fmac_f32_e32 v111, v47, v143
	v_fmac_f32_e32 v112, v44, v159
	v_fmac_f32_e32 v113, v45, v159
	v_fmac_f32_e32 v114, v46, v159
	v_fmac_f32_e32 v115, v47, v159
	v_fmac_f32_e32 v116, v44, v187
	v_fmac_f32_e32 v117, v45, v187
	v_fmac_f32_e32 v118, v46, v187
	v_fmac_f32_e32 v119, v47, v187
	s_waitcnt vmcnt(17)
	v_fmac_f32_e32 v100, v48, v88
	v_fmac_f32_e32 v101, v49, v88
	v_fmac_f32_e32 v102, v50, v88
	v_fmac_f32_e32 v103, v51, v88
	v_fmac_f32_e32 v104, v48, v128
	v_fmac_f32_e32 v105, v49, v128
	v_fmac_f32_e32 v106, v50, v128
	v_fmac_f32_e32 v107, v51, v128
	v_fmac_f32_e32 v108, v48, v144
	v_fmac_f32_e32 v109, v49, v144
	v_fmac_f32_e32 v110, v50, v144
	v_fmac_f32_e32 v111, v51, v144
	v_fmac_f32_e32 v112, v48, v160
	v_fmac_f32_e32 v113, v49, v160
	v_fmac_f32_e32 v114, v50, v160
	v_fmac_f32_e32 v115, v51, v160
	v_fmac_f32_e32 v116, v48, v188
	v_fmac_f32_e32 v117, v49, v188
	v_fmac_f32_e32 v118, v50, v188
	v_fmac_f32_e32 v119, v51, v188
	s_waitcnt vmcnt(16)
	v_fmac_f32_e32 v100, v52, v89
	v_fmac_f32_e32 v101, v53, v89
	v_fmac_f32_e32 v102, v54, v89
	v_fmac_f32_e32 v103, v55, v89
	v_fmac_f32_e32 v104, v52, v129
	v_fmac_f32_e32 v105, v53, v129
	v_fmac_f32_e32 v106, v54, v129
	v_fmac_f32_e32 v107, v55, v129
	v_fmac_f32_e32 v108, v52, v145
	v_fmac_f32_e32 v109, v53, v145
	v_fmac_f32_e32 v110, v54, v145
	v_fmac_f32_e32 v111, v55, v145
	v_fmac_f32_e32 v112, v52, v161
	v_fmac_f32_e32 v113, v53, v161
	v_fmac_f32_e32 v114, v54, v161
	v_fmac_f32_e32 v115, v55, v161
	v_fmac_f32_e32 v116, v52, v189
	v_fmac_f32_e32 v117, v53, v189
	v_fmac_f32_e32 v118, v54, v189
	v_fmac_f32_e32 v119, v55, v189
	s_waitcnt vmcnt(15)
	v_fmac_f32_e32 v100, v56, v90
	v_fmac_f32_e32 v101, v57, v90
	v_fmac_f32_e32 v102, v58, v90
	v_fmac_f32_e32 v103, v59, v90
	v_fmac_f32_e32 v104, v56, v130
	v_fmac_f32_e32 v105, v57, v130
	v_fmac_f32_e32 v106, v58, v130
	v_fmac_f32_e32 v107, v59, v130
	v_fmac_f32_e32 v108, v56, v146
	v_fmac_f32_e32 v109, v57, v146
	v_fmac_f32_e32 v110, v58, v146
	v_fmac_f32_e32 v111, v59, v146
	v_fmac_f32_e32 v112, v56, v162
	v_fmac_f32_e32 v113, v57, v162
	v_fmac_f32_e32 v114, v58, v162
	v_fmac_f32_e32 v115, v59, v162
	v_fmac_f32_e32 v116, v56, v190
	v_fmac_f32_e32 v117, v57, v190
	v_fmac_f32_e32 v118, v58, v190
	v_fmac_f32_e32 v119, v59, v190
	s_waitcnt vmcnt(14)
	v_fmac_f32_e32 v100, v60, v91
	v_fmac_f32_e32 v101, v61, v91
	v_fmac_f32_e32 v102, v62, v91
	v_fmac_f32_e32 v103, v63, v91
	v_fmac_f32_e32 v104, v60, v131
	v_fmac_f32_e32 v105, v61, v131
	v_fmac_f32_e32 v106, v62, v131
	v_fmac_f32_e32 v107, v63, v131
	v_fmac_f32_e32 v108, v60, v147
	v_fmac_f32_e32 v109, v61, v147
	v_fmac_f32_e32 v110, v62, v147
	v_fmac_f32_e32 v111, v63, v147
	v_fmac_f32_e32 v112, v60, v163
	v_fmac_f32_e32 v113, v61, v163
	v_fmac_f32_e32 v114, v62, v163
	v_fmac_f32_e32 v115, v63, v163
	v_fmac_f32_e32 v116, v60, v191
	v_fmac_f32_e32 v117, v61, v191
	v_fmac_f32_e32 v118, v62, v191
	v_fmac_f32_e32 v119, v63, v191
	s_waitcnt vmcnt(13)
	v_fmac_f32_e32 v100, v64, v92
	v_fmac_f32_e32 v101, v65, v92
	v_fmac_f32_e32 v102, v66, v92
	v_fmac_f32_e32 v103, v67, v92
	v_fmac_f32_e32 v104, v64, v132
	v_fmac_f32_e32 v105, v65, v132
	v_fmac_f32_e32 v106, v66, v132
	v_fmac_f32_e32 v107, v67, v132
	v_fmac_f32_e32 v108, v64, v148
	v_fmac_f32_e32 v109, v65, v148
	v_fmac_f32_e32 v110, v66, v148
	v_fmac_f32_e32 v111, v67, v148
	v_fmac_f32_e32 v112, v64, v164
	v_fmac_f32_e32 v113, v65, v164
	v_fmac_f32_e32 v114, v66, v164
	v_fmac_f32_e32 v115, v67, v164
	v_fmac_f32_e32 v116, v64, v192
	v_fmac_f32_e32 v117, v65, v192
	v_fmac_f32_e32 v118, v66, v192
	v_fmac_f32_e32 v119, v67, v192
	s_waitcnt vmcnt(12)
	v_fmac_f32_e32 v100, v68, v93
	v_fmac_f32_e32 v101, v69, v93
	v_fmac_f32_e32 v102, v70, v93
	v_fmac_f32_e32 v103, v71, v93
	v_fmac_f32_e32 v104, v68, v133
	v_fmac_f32_e32 v105, v69, v133
	v_fmac_f32_e32 v106, v70, v133
	v_fmac_f32_e32 v107, v71, v133
	v_fmac_f32_e32 v108, v68, v149
	v_fmac_f32_e32 v109, v69, v149
	v_fmac_f32_e32 v110, v70, v149
	v_fmac_f32_e32 v111, v71, v149
	v_fmac_f32_e32 v112, v68, v165
	v_fmac_f32_e32 v113, v69, v165
	v_fmac_f32_e32 v114, v70, v165
	v_fmac_f32_e32 v115, v71, v165
	v_fmac_f32_e32 v116, v68, v193
	v_fmac_f32_e32 v117, v69, v193
	v_fmac_f32_e32 v118, v70, v193
	v_fmac_f32_e32 v119, v71, v193
	s_waitcnt vmcnt(11)
	v_fmac_f32_e32 v100, v72, v94
	v_fmac_f32_e32 v101, v73, v94
	v_fmac_f32_e32 v102, v74, v94
	v_fmac_f32_e32 v103, v75, v94
	v_fmac_f32_e32 v104, v72, v134
	v_fmac_f32_e32 v105, v73, v134
	v_fmac_f32_e32 v106, v74, v134
	v_fmac_f32_e32 v107, v75, v134
	v_fmac_f32_e32 v108, v72, v150
	v_fmac_f32_e32 v109, v73, v150
	v_fmac_f32_e32 v110, v74, v150
	v_fmac_f32_e32 v111, v75, v150
	v_fmac_f32_e32 v112, v72, v166
	v_fmac_f32_e32 v113, v73, v166
	v_fmac_f32_e32 v114, v74, v166
	v_fmac_f32_e32 v115, v75, v166
	v_fmac_f32_e32 v116, v72, v194
	v_fmac_f32_e32 v117, v73, v194
	v_fmac_f32_e32 v118, v74, v194
	v_fmac_f32_e32 v119, v75, v194
	s_waitcnt vmcnt(10)
	v_fmac_f32_e32 v100, v76, v95
	v_fmac_f32_e32 v101, v77, v95
	v_fmac_f32_e32 v102, v78, v95
	v_fmac_f32_e32 v103, v79, v95
	v_fmac_f32_e32 v104, v76, v135
	v_fmac_f32_e32 v105, v77, v135
	v_fmac_f32_e32 v106, v78, v135
	v_fmac_f32_e32 v107, v79, v135
	v_fmac_f32_e32 v108, v76, v151
	v_fmac_f32_e32 v109, v77, v151
	v_fmac_f32_e32 v110, v78, v151
	v_fmac_f32_e32 v111, v79, v151
	v_fmac_f32_e32 v112, v76, v167
	v_fmac_f32_e32 v113, v77, v167
	v_fmac_f32_e32 v114, v78, v167
	v_fmac_f32_e32 v115, v79, v167
	v_fmac_f32_e32 v116, v76, v195
	v_fmac_f32_e32 v117, v77, v195
	v_fmac_f32_e32 v118, v78, v195
	v_fmac_f32_e32 v119, v79, v195
	global_load_dwordx4 v[16:19], v14, s[20:21] nt
	s_add_u32 s20, s20, 0x6000
	s_addc_u32 s21, s21, 0
	global_load_dwordx4 v[20:23], v14, s[20:21] nt
	s_add_u32 s20, s20, 0x6000
	s_addc_u32 s21, s21, 0
	global_load_dwordx4 v[24:27], v14, s[20:21] nt
	s_add_u32 s20, s20, 0x6000
	s_addc_u32 s21, s21, 0
	global_load_dwordx4 v[28:31], v14, s[20:21] nt
	s_add_u32 s20, s20, 0x6000
	s_addc_u32 s21, s21, 0
	global_load_dwordx4 v[32:35], v14, s[20:21] nt
	s_add_u32 s20, s20, 0x6000
	s_addc_u32 s21, s21, 0
	global_load_dwordx4 v[36:39], v14, s[20:21] nt
	s_add_u32 s20, s20, 0x6000
	s_addc_u32 s21, s21, 0
	ds_read_b128 v[80:83], v11 offset:64
	ds_read_b128 v[84:87], v11 offset:80
	ds_read_b128 v[88:91], v11 offset:96
	ds_read_b128 v[92:95], v11 offset:112
	ds_read_b128 v[120:123], v11 offset:4160
	ds_read_b128 v[124:127], v11 offset:4176
	ds_read_b128 v[128:131], v11 offset:4192
	ds_read_b128 v[132:135], v11 offset:4208
	ds_read_b128 v[136:139], v11 offset:8256
	ds_read_b128 v[140:143], v11 offset:8272
	ds_read_b128 v[144:147], v11 offset:8288
	ds_read_b128 v[148:151], v11 offset:8304
	ds_read_b128 v[152:155], v11 offset:12352
	ds_read_b128 v[156:159], v11 offset:12368
	ds_read_b128 v[160:163], v11 offset:12384
	ds_read_b128 v[164:167], v11 offset:12400
	ds_read_b128 v[180:183], v11 offset:16448
	ds_read_b128 v[184:187], v11 offset:16464
	ds_read_b128 v[188:191], v11 offset:16480
	ds_read_b128 v[192:195], v11 offset:16496
	s_waitcnt lgkmcnt(0)
	s_waitcnt vmcnt(15)
	v_fmac_f32_e32 v100, v196, v80
	v_fmac_f32_e32 v101, v197, v80
	v_fmac_f32_e32 v102, v198, v80
	v_fmac_f32_e32 v103, v199, v80
	v_fmac_f32_e32 v104, v196, v120
	v_fmac_f32_e32 v105, v197, v120
	v_fmac_f32_e32 v106, v198, v120
	v_fmac_f32_e32 v107, v199, v120
	v_fmac_f32_e32 v108, v196, v136
	v_fmac_f32_e32 v109, v197, v136
	v_fmac_f32_e32 v110, v198, v136
	v_fmac_f32_e32 v111, v199, v136
	v_fmac_f32_e32 v112, v196, v152
	v_fmac_f32_e32 v113, v197, v152
	v_fmac_f32_e32 v114, v198, v152
	v_fmac_f32_e32 v115, v199, v152
	v_fmac_f32_e32 v116, v196, v180
	v_fmac_f32_e32 v117, v197, v180
	v_fmac_f32_e32 v118, v198, v180
	v_fmac_f32_e32 v119, v199, v180
	s_waitcnt vmcnt(14)
	v_fmac_f32_e32 v100, v200, v81
	v_fmac_f32_e32 v101, v201, v81
	v_fmac_f32_e32 v102, v202, v81
	v_fmac_f32_e32 v103, v203, v81
	v_fmac_f32_e32 v104, v200, v121
	v_fmac_f32_e32 v105, v201, v121
	v_fmac_f32_e32 v106, v202, v121
	v_fmac_f32_e32 v107, v203, v121
	v_fmac_f32_e32 v108, v200, v137
	v_fmac_f32_e32 v109, v201, v137
	v_fmac_f32_e32 v110, v202, v137
	v_fmac_f32_e32 v111, v203, v137
	v_fmac_f32_e32 v112, v200, v153
	v_fmac_f32_e32 v113, v201, v153
	v_fmac_f32_e32 v114, v202, v153
	v_fmac_f32_e32 v115, v203, v153
	v_fmac_f32_e32 v116, v200, v181
	v_fmac_f32_e32 v117, v201, v181
	v_fmac_f32_e32 v118, v202, v181
	v_fmac_f32_e32 v119, v203, v181
	s_waitcnt vmcnt(13)
	v_fmac_f32_e32 v100, v204, v82
	v_fmac_f32_e32 v101, v205, v82
	v_fmac_f32_e32 v102, v206, v82
	v_fmac_f32_e32 v103, v207, v82
	v_fmac_f32_e32 v104, v204, v122
	v_fmac_f32_e32 v105, v205, v122
	v_fmac_f32_e32 v106, v206, v122
	v_fmac_f32_e32 v107, v207, v122
	v_fmac_f32_e32 v108, v204, v138
	v_fmac_f32_e32 v109, v205, v138
	v_fmac_f32_e32 v110, v206, v138
	v_fmac_f32_e32 v111, v207, v138
	v_fmac_f32_e32 v112, v204, v154
	v_fmac_f32_e32 v113, v205, v154
	v_fmac_f32_e32 v114, v206, v154
	v_fmac_f32_e32 v115, v207, v154
	v_fmac_f32_e32 v116, v204, v182
	v_fmac_f32_e32 v117, v205, v182
	v_fmac_f32_e32 v118, v206, v182
	v_fmac_f32_e32 v119, v207, v182
	s_waitcnt vmcnt(12)
	v_fmac_f32_e32 v100, v208, v83
	v_fmac_f32_e32 v101, v209, v83
	v_fmac_f32_e32 v102, v210, v83
	v_fmac_f32_e32 v103, v211, v83
	v_fmac_f32_e32 v104, v208, v123
	v_fmac_f32_e32 v105, v209, v123
	v_fmac_f32_e32 v106, v210, v123
	v_fmac_f32_e32 v107, v211, v123
	v_fmac_f32_e32 v108, v208, v139
	v_fmac_f32_e32 v109, v209, v139
	v_fmac_f32_e32 v110, v210, v139
	v_fmac_f32_e32 v111, v211, v139
	v_fmac_f32_e32 v112, v208, v155
	v_fmac_f32_e32 v113, v209, v155
	v_fmac_f32_e32 v114, v210, v155
	v_fmac_f32_e32 v115, v211, v155
	v_fmac_f32_e32 v116, v208, v183
	v_fmac_f32_e32 v117, v209, v183
	v_fmac_f32_e32 v118, v210, v183
	v_fmac_f32_e32 v119, v211, v183
	s_waitcnt vmcnt(11)
	v_fmac_f32_e32 v100, v212, v84
	v_fmac_f32_e32 v101, v213, v84
	v_fmac_f32_e32 v102, v214, v84
	v_fmac_f32_e32 v103, v215, v84
	v_fmac_f32_e32 v104, v212, v124
	v_fmac_f32_e32 v105, v213, v124
	v_fmac_f32_e32 v106, v214, v124
	v_fmac_f32_e32 v107, v215, v124
	v_fmac_f32_e32 v108, v212, v140
	v_fmac_f32_e32 v109, v213, v140
	v_fmac_f32_e32 v110, v214, v140
	v_fmac_f32_e32 v111, v215, v140
	v_fmac_f32_e32 v112, v212, v156
	v_fmac_f32_e32 v113, v213, v156
	v_fmac_f32_e32 v114, v214, v156
	v_fmac_f32_e32 v115, v215, v156
	v_fmac_f32_e32 v116, v212, v184
	v_fmac_f32_e32 v117, v213, v184
	v_fmac_f32_e32 v118, v214, v184
	v_fmac_f32_e32 v119, v215, v184
	s_waitcnt vmcnt(10)
	v_fmac_f32_e32 v100, v216, v85
	v_fmac_f32_e32 v101, v217, v85
	v_fmac_f32_e32 v102, v218, v85
	v_fmac_f32_e32 v103, v219, v85
	v_fmac_f32_e32 v104, v216, v125
	v_fmac_f32_e32 v105, v217, v125
	v_fmac_f32_e32 v106, v218, v125
	v_fmac_f32_e32 v107, v219, v125
	v_fmac_f32_e32 v108, v216, v141
	v_fmac_f32_e32 v109, v217, v141
	v_fmac_f32_e32 v110, v218, v141
	v_fmac_f32_e32 v111, v219, v141
	v_fmac_f32_e32 v112, v216, v157
	v_fmac_f32_e32 v113, v217, v157
	v_fmac_f32_e32 v114, v218, v157
	v_fmac_f32_e32 v115, v219, v157
	v_fmac_f32_e32 v116, v216, v185
	v_fmac_f32_e32 v117, v217, v185
	v_fmac_f32_e32 v118, v218, v185
	v_fmac_f32_e32 v119, v219, v185
	s_waitcnt vmcnt(9)
	v_fmac_f32_e32 v100, v220, v86
	v_fmac_f32_e32 v101, v221, v86
	v_fmac_f32_e32 v102, v222, v86
	v_fmac_f32_e32 v103, v223, v86
	v_fmac_f32_e32 v104, v220, v126
	v_fmac_f32_e32 v105, v221, v126
	v_fmac_f32_e32 v106, v222, v126
	v_fmac_f32_e32 v107, v223, v126
	v_fmac_f32_e32 v108, v220, v142
	v_fmac_f32_e32 v109, v221, v142
	v_fmac_f32_e32 v110, v222, v142
	v_fmac_f32_e32 v111, v223, v142
	v_fmac_f32_e32 v112, v220, v158
	v_fmac_f32_e32 v113, v221, v158
	v_fmac_f32_e32 v114, v222, v158
	v_fmac_f32_e32 v115, v223, v158
	v_fmac_f32_e32 v116, v220, v186
	v_fmac_f32_e32 v117, v221, v186
	v_fmac_f32_e32 v118, v222, v186
	v_fmac_f32_e32 v119, v223, v186
	s_waitcnt vmcnt(8)
	v_fmac_f32_e32 v100, v224, v87
	v_fmac_f32_e32 v101, v225, v87
	v_fmac_f32_e32 v102, v226, v87
	v_fmac_f32_e32 v103, v227, v87
	v_fmac_f32_e32 v104, v224, v127
	v_fmac_f32_e32 v105, v225, v127
	v_fmac_f32_e32 v106, v226, v127
	v_fmac_f32_e32 v107, v227, v127
	v_fmac_f32_e32 v108, v224, v143
	v_fmac_f32_e32 v109, v225, v143
	v_fmac_f32_e32 v110, v226, v143
	v_fmac_f32_e32 v111, v227, v143
	v_fmac_f32_e32 v112, v224, v159
	v_fmac_f32_e32 v113, v225, v159
	v_fmac_f32_e32 v114, v226, v159
	v_fmac_f32_e32 v115, v227, v159
	v_fmac_f32_e32 v116, v224, v187
	v_fmac_f32_e32 v117, v225, v187
	v_fmac_f32_e32 v118, v226, v187
	v_fmac_f32_e32 v119, v227, v187
	s_waitcnt vmcnt(7)
	v_fmac_f32_e32 v100, v228, v88
	v_fmac_f32_e32 v101, v229, v88
	v_fmac_f32_e32 v102, v230, v88
	v_fmac_f32_e32 v103, v231, v88
	v_fmac_f32_e32 v104, v228, v128
	v_fmac_f32_e32 v105, v229, v128
	v_fmac_f32_e32 v106, v230, v128
	v_fmac_f32_e32 v107, v231, v128
	v_fmac_f32_e32 v108, v228, v144
	v_fmac_f32_e32 v109, v229, v144
	v_fmac_f32_e32 v110, v230, v144
	v_fmac_f32_e32 v111, v231, v144
	v_fmac_f32_e32 v112, v228, v160
	v_fmac_f32_e32 v113, v229, v160
	v_fmac_f32_e32 v114, v230, v160
	v_fmac_f32_e32 v115, v231, v160
	v_fmac_f32_e32 v116, v228, v188
	v_fmac_f32_e32 v117, v229, v188
	v_fmac_f32_e32 v118, v230, v188
	v_fmac_f32_e32 v119, v231, v188
	s_waitcnt vmcnt(6)
	v_fmac_f32_e32 v100, v96, v89
	v_fmac_f32_e32 v101, v97, v89
	v_fmac_f32_e32 v102, v98, v89
	v_fmac_f32_e32 v103, v99, v89
	v_fmac_f32_e32 v104, v96, v129
	v_fmac_f32_e32 v105, v97, v129
	v_fmac_f32_e32 v106, v98, v129
	v_fmac_f32_e32 v107, v99, v129
	v_fmac_f32_e32 v108, v96, v145
	v_fmac_f32_e32 v109, v97, v145
	v_fmac_f32_e32 v110, v98, v145
	v_fmac_f32_e32 v111, v99, v145
	v_fmac_f32_e32 v112, v96, v161
	v_fmac_f32_e32 v113, v97, v161
	v_fmac_f32_e32 v114, v98, v161
	v_fmac_f32_e32 v115, v99, v161
	v_fmac_f32_e32 v116, v96, v189
	v_fmac_f32_e32 v117, v97, v189
	v_fmac_f32_e32 v118, v98, v189
	v_fmac_f32_e32 v119, v99, v189
	s_waitcnt vmcnt(5)
	v_fmac_f32_e32 v100, v16, v90
	v_fmac_f32_e32 v101, v17, v90
	v_fmac_f32_e32 v102, v18, v90
	v_fmac_f32_e32 v103, v19, v90
	v_fmac_f32_e32 v104, v16, v130
	v_fmac_f32_e32 v105, v17, v130
	v_fmac_f32_e32 v106, v18, v130
	v_fmac_f32_e32 v107, v19, v130
	v_fmac_f32_e32 v108, v16, v146
	v_fmac_f32_e32 v109, v17, v146
	v_fmac_f32_e32 v110, v18, v146
	v_fmac_f32_e32 v111, v19, v146
	v_fmac_f32_e32 v112, v16, v162
	v_fmac_f32_e32 v113, v17, v162
	v_fmac_f32_e32 v114, v18, v162
	v_fmac_f32_e32 v115, v19, v162
	v_fmac_f32_e32 v116, v16, v190
	v_fmac_f32_e32 v117, v17, v190
	v_fmac_f32_e32 v118, v18, v190
	v_fmac_f32_e32 v119, v19, v190
	s_waitcnt vmcnt(4)
	v_fmac_f32_e32 v100, v20, v91
	v_fmac_f32_e32 v101, v21, v91
	v_fmac_f32_e32 v102, v22, v91
	v_fmac_f32_e32 v103, v23, v91
	v_fmac_f32_e32 v104, v20, v131
	v_fmac_f32_e32 v105, v21, v131
	v_fmac_f32_e32 v106, v22, v131
	v_fmac_f32_e32 v107, v23, v131
	v_fmac_f32_e32 v108, v20, v147
	v_fmac_f32_e32 v109, v21, v147
	v_fmac_f32_e32 v110, v22, v147
	v_fmac_f32_e32 v111, v23, v147
	v_fmac_f32_e32 v112, v20, v163
	v_fmac_f32_e32 v113, v21, v163
	v_fmac_f32_e32 v114, v22, v163
	v_fmac_f32_e32 v115, v23, v163
	v_fmac_f32_e32 v116, v20, v191
	v_fmac_f32_e32 v117, v21, v191
	v_fmac_f32_e32 v118, v22, v191
	v_fmac_f32_e32 v119, v23, v191
	s_waitcnt vmcnt(3)
	v_fmac_f32_e32 v100, v24, v92
	v_fmac_f32_e32 v101, v25, v92
	v_fmac_f32_e32 v102, v26, v92
	v_fmac_f32_e32 v103, v27, v92
	v_fmac_f32_e32 v104, v24, v132
	v_fmac_f32_e32 v105, v25, v132
	v_fmac_f32_e32 v106, v26, v132
	v_fmac_f32_e32 v107, v27, v132
	v_fmac_f32_e32 v108, v24, v148
	v_fmac_f32_e32 v109, v25, v148
	v_fmac_f32_e32 v110, v26, v148
	v_fmac_f32_e32 v111, v27, v148
	v_fmac_f32_e32 v112, v24, v164
	v_fmac_f32_e32 v113, v25, v164
	v_fmac_f32_e32 v114, v26, v164
	v_fmac_f32_e32 v115, v27, v164
	v_fmac_f32_e32 v116, v24, v192
	v_fmac_f32_e32 v117, v25, v192
	v_fmac_f32_e32 v118, v26, v192
	v_fmac_f32_e32 v119, v27, v192
	s_waitcnt vmcnt(2)
	v_fmac_f32_e32 v100, v28, v93
	v_fmac_f32_e32 v101, v29, v93
	v_fmac_f32_e32 v102, v30, v93
	v_fmac_f32_e32 v103, v31, v93
	v_fmac_f32_e32 v104, v28, v133
	v_fmac_f32_e32 v105, v29, v133
	v_fmac_f32_e32 v106, v30, v133
	v_fmac_f32_e32 v107, v31, v133
	v_fmac_f32_e32 v108, v28, v149
	v_fmac_f32_e32 v109, v29, v149
	v_fmac_f32_e32 v110, v30, v149
	v_fmac_f32_e32 v111, v31, v149
	v_fmac_f32_e32 v112, v28, v165
	v_fmac_f32_e32 v113, v29, v165
	v_fmac_f32_e32 v114, v30, v165
	v_fmac_f32_e32 v115, v31, v165
	v_fmac_f32_e32 v116, v28, v193
	v_fmac_f32_e32 v117, v29, v193
	v_fmac_f32_e32 v118, v30, v193
	v_fmac_f32_e32 v119, v31, v193
	s_waitcnt vmcnt(1)
	v_fmac_f32_e32 v100, v32, v94
	v_fmac_f32_e32 v101, v33, v94
	v_fmac_f32_e32 v102, v34, v94
	v_fmac_f32_e32 v103, v35, v94
	v_fmac_f32_e32 v104, v32, v134
	v_fmac_f32_e32 v105, v33, v134
	v_fmac_f32_e32 v106, v34, v134
	v_fmac_f32_e32 v107, v35, v134
	v_fmac_f32_e32 v108, v32, v150
	v_fmac_f32_e32 v109, v33, v150
	v_fmac_f32_e32 v110, v34, v150
	v_fmac_f32_e32 v111, v35, v150
	v_fmac_f32_e32 v112, v32, v166
	v_fmac_f32_e32 v113, v33, v166
	v_fmac_f32_e32 v114, v34, v166
	v_fmac_f32_e32 v115, v35, v166
	v_fmac_f32_e32 v116, v32, v194
	v_fmac_f32_e32 v117, v33, v194
	v_fmac_f32_e32 v118, v34, v194
	v_fmac_f32_e32 v119, v35, v194
	s_waitcnt vmcnt(0)
	v_fmac_f32_e32 v100, v36, v95
	v_fmac_f32_e32 v101, v37, v95
	v_fmac_f32_e32 v102, v38, v95
	v_fmac_f32_e32 v103, v39, v95
	v_fmac_f32_e32 v104, v36, v135
	v_fmac_f32_e32 v105, v37, v135
	v_fmac_f32_e32 v106, v38, v135
	v_fmac_f32_e32 v107, v39, v135
	v_fmac_f32_e32 v108, v36, v151
	v_fmac_f32_e32 v109, v37, v151
	v_fmac_f32_e32 v110, v38, v151
	v_fmac_f32_e32 v111, v39, v151
	v_fmac_f32_e32 v112, v36, v167
	v_fmac_f32_e32 v113, v37, v167
	v_fmac_f32_e32 v114, v38, v167
	v_fmac_f32_e32 v115, v39, v167
	v_fmac_f32_e32 v116, v36, v195
	v_fmac_f32_e32 v117, v37, v195
	v_fmac_f32_e32 v118, v38, v195
	v_fmac_f32_e32 v119, v39, v195
	v_lshl_add_u32 v11, s16, 2, v13
	v_mul_u32_u24_e32 v11, 0x500, v11
	v_lshl_add_u32 v11, v12, 4, v11
	ds_write_b128 v11, v[100:103] offset:20480
	ds_write_b128 v11, v[104:107] offset:20736
	ds_write_b128 v11, v[108:111] offset:20992
	ds_write_b128 v11, v[112:115] offset:21248
	ds_write_b128 v11, v[116:119] offset:21504
	s_waitcnt lgkmcnt(0)
	s_barrier
	v_cmp_gt_u32_e32 vcc, 0x140, v1
	s_and_saveexec_b64 s[16:17], vcc
	s_cbranch_execz .Lgv_fin
	v_and_b32_e32 v12, 63, v1
	v_lshrrev_b32_e32 v13, 6, v1
	v_add_u32_e32 v14, s15, v12
	s_mul_i32 s20, s14, 0x1800
	v_add_u32_e32 v2, s20, v14
	v_lshlrev_b32_e32 v2, 2, v2
	global_load_dword v3, v2, s[34:35]
	v_lshlrev_b32_e32 v11, 8, v13
	v_lshl_add_u32 v11, v12, 2, v11
	ds_read_b32 v16, v11 offset:20480
	ds_read_b32 v17, v11 offset:21760
	ds_read_b32 v18, v11 offset:23040
	ds_read_b32 v19, v11 offset:24320
	ds_read_b32 v20, v11 offset:25600
	ds_read_b32 v21, v11 offset:26880
	ds_read_b32 v22, v11 offset:28160
	ds_read_b32 v23, v11 offset:29440
	ds_read_b32 v24, v11 offset:30720
	ds_read_b32 v25, v11 offset:32000
	ds_read_b32 v26, v11 offset:33280
	ds_read_b32 v27, v11 offset:34560
	ds_read_b32 v28, v11 offset:35840
	ds_read_b32 v29, v11 offset:37120
	ds_read_b32 v30, v11 offset:38400
	ds_read_b32 v31, v11 offset:39680
	ds_read_b32 v32, v11 offset:40960
	ds_read_b32 v33, v11 offset:42240
	ds_read_b32 v34, v11 offset:43520
	ds_read_b32 v35, v11 offset:44800
	ds_read_b32 v36, v11 offset:46080
	ds_read_b32 v37, v11 offset:47360
	ds_read_b32 v38, v11 offset:48640
	ds_read_b32 v39, v11 offset:49920
	ds_read_b32 v40, v11 offset:51200
	ds_read_b32 v41, v11 offset:52480
	ds_read_b32 v42, v11 offset:53760
	ds_read_b32 v43, v11 offset:55040
	ds_read_b32 v44, v11 offset:56320
	ds_read_b32 v45, v11 offset:57600
	ds_read_b32 v46, v11 offset:58880
	ds_read_b32 v47, v11 offset:60160
	s_waitcnt vmcnt(0)
	s_waitcnt lgkmcnt(15)
	v_add_f32_e32 v3, v3, v16
	s_waitcnt lgkmcnt(15)
	v_add_f32_e32 v3, v3, v17
	s_waitcnt lgkmcnt(15)
	v_add_f32_e32 v3, v3, v18
	s_waitcnt lgkmcnt(15)
	v_add_f32_e32 v3, v3, v19
	s_waitcnt lgkmcnt(15)
	v_add_f32_e32 v3, v3, v20
	s_waitcnt lgkmcnt(15)
	v_add_f32_e32 v3, v3, v21
	s_waitcnt lgkmcnt(15)
	v_add_f32_e32 v3, v3, v22
	s_waitcnt lgkmcnt(15)
	v_add_f32_e32 v3, v3, v23
	s_waitcnt lgkmcnt(15)
	v_add_f32_e32 v3, v3, v24
	s_waitcnt lgkmcnt(15)
	v_add_f32_e32 v3, v3, v25
	s_waitcnt lgkmcnt(15)
	v_add_f32_e32 v3, v3, v26
	s_waitcnt lgkmcnt(15)
	v_add_f32_e32 v3, v3, v27
	s_waitcnt lgkmcnt(15)
	v_add_f32_e32 v3, v3, v28
	s_waitcnt lgkmcnt(15)
	v_add_f32_e32 v3, v3, v29
	s_waitcnt lgkmcnt(15)
	v_add_f32_e32 v3, v3, v30
	s_waitcnt lgkmcnt(15)
	v_add_f32_e32 v3, v3, v31
	s_waitcnt lgkmcnt(15)
	v_add_f32_e32 v3, v3, v32
	s_waitcnt lgkmcnt(14)
	v_add_f32_e32 v3, v3, v33
	s_waitcnt lgkmcnt(13)
	v_add_f32_e32 v3, v3, v34
	s_waitcnt lgkmcnt(12)
	v_add_f32_e32 v3, v3, v35
	s_waitcnt lgkmcnt(11)
	v_add_f32_e32 v3, v3, v36
	s_waitcnt lgkmcnt(10)
	v_add_f32_e32 v3, v3, v37
	s_waitcnt lgkmcnt(9)
	v_add_f32_e32 v3, v3, v38
	s_waitcnt lgkmcnt(8)
	v_add_f32_e32 v3, v3, v39
	s_waitcnt lgkmcnt(7)
	v_add_f32_e32 v3, v3, v40
	s_waitcnt lgkmcnt(6)
	v_add_f32_e32 v3, v3, v41
	s_waitcnt lgkmcnt(5)
	v_add_f32_e32 v3, v3, v42
	s_waitcnt lgkmcnt(4)
	v_add_f32_e32 v3, v3, v43
	s_waitcnt lgkmcnt(3)
	v_add_f32_e32 v3, v3, v44
	s_waitcnt lgkmcnt(2)
	v_add_f32_e32 v3, v3, v45
	s_waitcnt lgkmcnt(1)
	v_add_f32_e32 v3, v3, v46
	s_waitcnt lgkmcnt(0)
	v_add_f32_e32 v3, v3, v47
	s_lshr_b32 s20, s15, 10
	v_and_b32_e32 v14, 0x3ff, v14
	s_mul_i32 s21, s14, 5
	v_add_u32_e32 v4, s21, v13
	v_mul_u32_u24_e32 v4, 0x1800, v4
	v_add_u32_e32 v4, v4, v14
	v_lshlrev_b32_e32 v4, 2, v4
	s_add_u32 s26, s10, 0x780000
	s_addc_u32 s27, s11, 0
	s_cmp_lg_u32 s20, 0
	s_cbranch_scc1 .Lgv_j0
	v_add_u32_e32 v4, 0x1000, v4
	global_store_dword v4, v3, s[26:27]
	s_branch .Lgv_fin
